# scan / up-projection order split by workgroup index bit 3 (half of every XCD) instead of bit 2 (XCD halves)
# speedup vs baseline: 1.0014x; 1.0005x over previous
;     __host__ __device__ void init(int N, int K, int G_, int c_, int mode_, int rev_ = 0) { so.init(128 * BM, N, K, G_, c_, rev_); nN = N / BM; mode = mode_; }
; #define LAUNDER() int tid = tid0; asm volatile("" : "+v"(tid)); int wg = blockIdx.x; asm volatile("" : "+s"(wg)); const int lane = tid & 63, wave = __builtin_amdgcn_readfirstlane(tid >> 6), gw = wg * NWAVES + wave, NGW = G * NWAVES; (void)lane; (void)wave; (void)gw; (void)NGW
; __global__ void __launch_bounds__(NTHR, 2) fwd_kernel(Args a) {
;     ...
;         { LAUNDER(); mlstm_scan(DC, DN, SC, wg, G, tid); }
;         __syncthreads();
;         { LAUNDER(); pg8::Gemm g{Z + ZQ, WUQ, MTOK, 768, 512}; pg8::StaticOrder S; S.init(MTOK, 768, 512, G, wg, 1);
;           pg8::EpiBf16<0, false, true, 512, false> E{QM, 768, nullptr, rs2, nullptr, 0};
;           pg8::gemm_phase<pg8::EpiBf16<0, false, true, 512, false>, pg8::StaticOrder, true, true, DINP>(L, g, S, E); }
;         { LAUNDER(); pg8::Gemm g{Z + ZKV, WUKV, MTOK, 1024, 256}; pg8::StaticOrder S; S.init(MTOK, 1024, 256, G, (wg + 116) % G, 1);
;           pg8::EpiBf16<0, false, true, 256, false> E{KVM, 1024, nullptr, rs2 + MTOK, nullptr, 0};
;           pg8::gemm_phase<pg8::EpiBf16<0, false, true, 256, false>, pg8::StaticOrder, true, true, DINP>(L, g, S, E); }
.LBB0_652:
	s_or_b64 exec, exec, s[2:3]
	s_waitcnt lgkmcnt(0)
	s_barrier
	s_mov_b32 s100, 0
	s_bitcmp1_b32 s48, 3
	s_cbranch_scc0 .Lscan_late_entry
	s_mov_b32 s100, 1
	s_branch .LBB0_729
